# p0: the x->X16 conversion (independent of the weight prep) moved ahead of the first grid barrier; half of the workgroups run it before their weight-prep items, the other half after
# baseline (speedup 1.0000x reference)
_Z8hpge_fwd6Params:
	s_load_dwordx8 s[72:79], s[0:1], 0x80
	s_load_dword s3, s[0:1], 0xa0
	s_add_u32 s4, s0, 0xa0
	s_addc_u32 s5, s1, 0
	s_mov_b32 s100, 2
	v_and_b32_e32 v232, 0x3ff, v0
	v_writelane_b32 v254, s4, 0
	v_readfirstlane_b32 s12, v232
	v_cmp_gt_u32_e32 vcc, 16, v232
	v_writelane_b32 v254, s5, 1
	s_and_saveexec_b64 s[4:5], vcc
	v_lshl_add_u32 v1, v232, 2, 0
	v_add_u32_e32 v1, 0x26bc0, v1
	v_mov_b32_e32 v2, 0
	ds_write_b32 v1, v2
	s_or_b64 exec, exec, s[4:5]
	s_waitcnt lgkmcnt(0)
	s_sub_i32 s4, s79, s78
	s_cmp_gt_i32 s4, 1
	s_cselect_b64 s[66:67], -1, 0
	s_cmp_lt_i32 s4, 2
	s_mov_b32 s33, 0
	v_cmp_eq_u32_e32 vcc, 0, v232
	s_mov_b32 s70, 0
	s_barrier
	s_cbranch_scc1 .LBB0_7
	s_getreg_b32 s4, hwreg(HW_REG_XCC_ID, 0, 4)
	s_and_b32 s33, s4, 15
	s_and_saveexec_b64 s[4:5], vcc
	s_cbranch_execz .LBB0_6
	s_mov_b64 s[6:7], exec
	v_mbcnt_lo_u32_b32 v1, s6, 0
	v_mbcnt_hi_u32_b32 v1, s7, v1
	v_cmp_eq_u32_e32 vcc, 0, v1
	s_and_b64 s[8:9], exec, vcc
	s_mov_b64 exec, s[8:9]
	s_cbranch_execz .LBB0_6
	s_lshl_b32 s8, s33, 8
	s_bcnt1_i32_b64 s6, s[6:7]
	v_mov_b32_e32 v1, s8
	v_mov_b32_e32 v2, s6
	global_atomic_add v1, v2, s[76:77] offset:1024

.LBB0_19:
	s_load_dwordx16 s[36:51], s[0:1], 0x0
	s_load_dwordx16 s[16:31], s[0:1], 0x40
	s_lshr_b32 s71, s12, 6
	s_cmp_lt_i32 s78, 1
	v_and_b32_e32 v233, 63, v232
	s_waitcnt lgkmcnt(0)
	v_writelane_b32 v254, s16, 2
	s_nop 1
	v_writelane_b32 v254, s17, 3
	v_writelane_b32 v254, s18, 4
	v_writelane_b32 v254, s19, 5
	v_writelane_b32 v254, s20, 6
	v_writelane_b32 v254, s21, 7
	v_writelane_b32 v254, s22, 8
	v_writelane_b32 v254, s23, 9
	v_writelane_b32 v254, s24, 10
	v_writelane_b32 v254, s25, 11
	v_writelane_b32 v254, s26, 12
	v_writelane_b32 v254, s27, 13
	v_writelane_b32 v254, s28, 14
	v_writelane_b32 v254, s29, 15
	v_writelane_b32 v254, s30, 16
	v_writelane_b32 v254, s31, 17
	s_cselect_b64 s[22:23], -1, 0
	s_cmp_gt_i32 s79, 0
	s_cselect_b64 s[0:1], -1, 0
	s_and_b64 s[0:1], s[22:23], s[0:1]
	s_andn2_b64 vcc, exec, s[0:1]
	s_cbranch_vccnz .LBB0_109
	s_mov_b32 s100, 0
	s_bitcmp1_b32 s2, 3
	s_cbranch_scc0 .Lp0_norm
	s_mov_b32 s100, 3
	s_mov_b64 s[98:99], s[22:23]
	v_writelane_b32 v253, s40, 0
	v_writelane_b32 v253, s41, 1
	s_branch .Lp0b_pro
.Lp0_norm:
	s_mov_b32 s54, s3
	v_mov_b32_e32 v2, v233
	s_mov_b32 s55, s2
	v_mov_b32_e32 v0, v232
	s_mov_b32 s16, s71
	s_mov_b64 s[24:25], 0
	s_add_u32 s63, s76, s24
	s_addc_u32 s96, s77, s25
	s_add_u32 s6, s63, 0x100000
	s_addc_u32 s7, s96, 0
	s_lshl_b32 s0, s55, 3
	s_add_i32 s12, s0, s16
	s_cmpk_gt_i32 s12, 0x19ff
	s_cbranch_scc1 .LBB0_53
	s_add_u32 s13, s63, 0x1900000
	s_mul_i32 s0, s16, 0x2100
	v_lshlrev_b32_e32 v3, 2, v2
	s_addc_u32 s14, s96, 0
	s_add_i32 s0, s0, 0
	v_ashrrev_i32_e32 v1, 3, v2
	v_and_b32_e32 v4, 28, v3
	s_movk_i32 s4, 0x84
	v_lshlrev_b32_e32 v6, 3, v2
	v_lshl_add_u32 v7, v4, 2, s0
	v_mul_lo_u32 v11, v1, s4
	v_and_b32_e32 v6, 56, v6
	v_mul_u32_u24_e32 v10, 0x84, v6
	v_lshlrev_b32_e32 v12, 2, v1
	v_add_u32_e32 v11, v7, v11
	s_lshl_b32 s15, s54, 3
	s_mov_b32 s1, 0
	v_mov_b32_e32 v5, 0
	v_add_u32_e32 v3, 8, v1
	v_add_u32_e32 v8, 16, v1
	v_add_u32_e32 v9, 24, v1
	v_add3_u32 v10, s0, v10, v12
	s_mov_b32 s17, 0x8000
	s_mov_b32 s18, 0x10000
	s_mov_b32 s19, 0x18000
	s_mov_b32 s20, 0x20000
	s_mov_b32 s21, 0x28000
	s_mov_b32 s26, 0x30000
	s_mov_b32 s27, 0x38000
	v_add_u32_e32 v12, 0x420, v11
	v_add_u32_e32 v13, 0x428, v11
	v_add_u32_e32 v14, 0x840, v11
	v_add_u32_e32 v15, 0x848, v11
	v_add_u32_e32 v16, 0xc60, v11
	v_add_u32_e32 v17, 0xc68, v11
	v_add_u32_e32 v18, 0x1080, v11
	v_add_u32_e32 v19, 0x1088, v11
	v_add_u32_e32 v20, 0x14a0, v11
	v_add_u32_e32 v21, 0x14a8, v11
	v_add_u32_e32 v22, 0x18c0, v11
	v_add_u32_e32 v23, 0x18c8, v11
	v_add_u32_e32 v24, 0x1ce0, v11
	v_add_u32_e32 v25, 0x1ce8, v11
	s_movk_i32 s28, 0xa00
	s_movk_i32 s29, 0x2c00
	v_lshlrev_b32_e32 v4, 2, v4
	v_lshlrev_b32_e32 v6, 1, v6
	s_branch .LBB0_24

.Lp0b_pro:
	v_mov_b32_e32 v73, v233
	s_mov_b32 s31, s2
	v_mov_b32_e32 v124, v232
	s_mov_b32 s0, s71
	s_mov_b32 s30, s3
	s_mov_b64 s[18:19], 0
	s_add_u32 s14, s76, s18
	s_addc_u32 s15, s77, s19
	s_lshl_b32 s26, s31, 3
	s_add_i32 s26, s26, s0
	s_add_u32 s16, s14, 0x100000
	s_addc_u32 s17, s15, 0
	s_bitcmp1_b32 s100, 0
	s_cbranch_scc1 .LBB0_173
	s_cmpk_gt_i32 s26, 0x2ff
	s_cbranch_scc1 .LBB0_173
	v_ashrrev_i32_e32 v2, 4, v73
	v_lshlrev_b32_e32 v0, 3, v2
	v_and_b32_e32 v72, 15, v73
	v_ashrrev_i32_e32 v1, 31, v0
	v_mov_b32_e32 v75, 0
	v_lshl_add_u64 v[76:77], v[0:1], 1, s[16:17]
	v_lshl_add_u64 v[0:1], v[0:1], 2, s[14:15]
	s_mov_b64 s[0:1], 0x2200000
	v_lshlrev_b32_e32 v87, 2, v2
	v_lshlrev_b32_e32 v74, 2, v72
	v_cmp_gt_u32_e32 vcc, 10, v72
	v_lshl_add_u64 v[78:79], v[0:1], 0, s[0:1]
	v_lshl_add_u64 v[0:1], s[14:15], 0, v[74:75]
	s_mov_b64 s[4:5], 0x2300000
	v_or_b32_e32 v74, 1, v87
	v_or_b32_e32 v88, 2, v87
	v_or_b32_e32 v89, 3, v87
	s_lshl_b32 s27, s30, 3
	s_mov_b32 s21, 0
	v_cndmask_b32_e32 v86, 0, v72, vcc
	v_cmp_lt_u32_e64 s[0:1], 9, v72
	v_lshl_add_u64 v[80:81], v[0:1], 0, s[4:5]
	v_cmp_gt_i32_e64 s[10:11], 3, v2
	v_cmp_gt_i32_e64 s[4:5], 10, v74
	v_cmp_gt_i32_e64 s[6:7], 10, v88
	v_cmp_gt_i32_e64 s[8:9], 10, v89
	s_movk_i32 s28, 0x3000
	s_mov_b32 s29, s26
	s_branch .LBB0_163

.Lp0_d3:
	s_cmp_eq_u32 s100, 3
	s_cbranch_scc0 .Lp0_d
	s_mov_b32 s100, 2
	s_mov_b64 s[22:23], s[98:99]
	v_readlane_b32 s40, v253, 0
	v_readlane_b32 s41, v253, 1
	s_branch .Lp0_norm
